# v51 + removed the remaining 12 back-to-back s_setprio 0/1 pairs in the out-proj and up-proj K-loops
# speedup vs baseline: 1.0071x; 1.0021x over previous
; #define PG8_STAGE(bufoff, gbase, voff) do { _Pragma("unroll") for (int _i = 0; _i < 2; ++_i) \
;         __builtin_amdgcn_global_load_lds((const unsigned*)((const char*)(gbase) + (voff)[_i]), (LAS unsigned*)(lds + (bufoff) + ldsw + _i * 8192), 16, 0, 0); } while (0)
; #define PG8_LDA(dst, b, h) do { _Pragma("unroll") for (int m = 0; m < 4; ++m) _Pragma("unroll") for (int k = 0; k < 2; ++k) dst[m][k] = *(const LAS bf16x8*)(lds + PG8_SA(b, h) + aoff + m * 2048 + k * 1024); } while (0)
; #define PG8_LDB(dst, b, h) do { _Pragma("unroll") for (int n = 0; n < 2; ++n) _Pragma("unroll") for (int k = 0; k < 2; ++k) dst[n][k] = *(const LAS bf16x8*)(lds + PG8_SB(b, h) + boff + n * 2048 + k * 1024); } while (0)
; #define PG8_WAIT_V(n) asm volatile("s_waitcnt vmcnt(" #n ")" ::: "memory")
; #define PG8_WAIT_L(n) asm volatile("s_waitcnt lgkmcnt(" #n ")" ::: "memory")
; #define PG8_BAR __builtin_amdgcn_s_barrier()
; #define PG8_SCHED __builtin_amdgcn_sched_barrier(0)
; template <class Epi, class Sched, bool HALFN = false>
; __device__ __forceinline__ void gemm_phase(LAS unsigned char* lds, const Gemm g, const Sched& S, const Epi& E, int wave_s) {
;     ...
;         const bool has_next = S.next(ui + 1, nxt);
;         const char* nA = has_next ? (const char*)g.A + (size_t)nxt.z * g.zA * 2 + (size_t)nxt.pm * tstep : cA; const char* nB = has_next ? (const char*)g.Bt + (size_t)nxt.z * g.zB * 2 + (size_t)nxt.pn * (HALFN ? hstep : tstep) : cB;
;         for (int t = 0; t < nt; t += 2) {
;             const bool last = (t == nt - 2);
;             const char* a1 = cA + (size_t)(t + 1) * kstep;
;             const char* a2 = last ? nA : cA + (size_t)(t + 2) * kstep; const char* b2 = last ? nB : cB + (size_t)(t + 2) * kstep;
;             const char* a3 = a2 + kstep; const char* b3 = b2 + kstep;
;             PG8_LDB(B0, 0, 0); if (!HALFN) PG8_LDB(B1, 0, 1); PG8_SCHED; PG8_LDA(At, 0, 0); PG8_STAGE(PG8_SA(1, 1), a1 + hstep, voffA);
;             PG8_WAIT_V(8); PG8_WAIT_L(0); PG8_BAR; PG8_MMA(0, 0, At, B0); if (!HALFN) PG8_MMA(0, 1, At, B1); PG8_BAR; PG8_SCHED;
;             PG8_LDA(At, 0, 1); PG8_STAGE(PG8_SB(0, 0), b2, voffB); PG8_STAGE(PG8_SB(0, 1), b2 + bh1, voffB); PG8_STAGE(PG8_SA(0, 0), a2, voffA);
;             PG8_WAIT_V(8); PG8_WAIT_L(0); PG8_BAR; PG8_MMA(1, 0, At, B0); if (!HALFN) PG8_MMA(1, 1, At, B1); PG8_BAR; PG8_SCHED;
.LBB0_515:
	s_add_u32 s35, s26, s34
	s_addc_u32 s46, s27, 0
	s_add_u32 s38, s35, 0x100
	s_addc_u32 s39, s46, 0
	s_and_b64 s[36:37], s[30:31], exec
	s_cselect_b32 s37, s17, s39
	s_cselect_b32 s36, s80, s38
	s_add_u32 s34, s24, s34
	s_addc_u32 s38, s25, 0
	s_add_u32 s34, s34, 0x100
	s_addc_u32 s38, s38, 0
	s_add_i32 s90, 0, 0x10000
	s_and_b64 s[30:31], s[30:31], exec
	s_cselect_b32 s39, s15, s38
	s_cselect_b32 s38, s81, s34
	s_add_i32 s31, 0, 0x14000
	s_add_u32 s56, s35, 0x10080
	s_addc_u32 s57, s46, 0
	s_add_i32 s89, s90, s52
	s_add_i32 m0, s23, 0xc000
	s_add_i32 s92, s23, 0xe000
	s_add_i32 s86, s89, 0x2000
	v_add_u32_e32 v139, s90, v1
	s_add_u32 s46, s38, 0x10000
	ds_read_b128 v[140:143], v139
	ds_read_b128 v[144:147], v139 offset:1024
	ds_read_b128 v[148:151], v139 offset:2048
	ds_read_b128 v[152:155], v139 offset:3072
	v_add_u32_e32 v139, s31, v1
	s_addc_u32 s47, s39, 0
	s_add_i32 s88, s31, s52
	ds_read_b128 v[156:159], v139
	ds_read_b128 v[160:163], v139 offset:1024
	ds_read_b128 v[164:167], v139 offset:2048
	ds_read_b128 v[168:171], v139 offset:3072
	s_add_i32 s87, s88, 0x2000
	s_add_i32 s85, 0, 0x18000
	s_add_i32 s84, 0, 0x1c000
	s_add_u32 s34, s36, 0x10000
	s_addc_u32 s35, s37, 0
	s_add_i32 s83, s85, s52
	s_add_i32 s82, s83, 0x2000
	s_add_u32 s30, s38, 0x10080
	s_addc_u32 s31, s39, 0
	s_add_i32 s91, s84, s52
	s_add_i32 s90, s91, 0x2000
	v_lshl_add_u64 v[196:197], s[56:57], 0, v[132:133]
	ds_read_b128 v[172:175], v138
	ds_read_b128 v[176:179], v138 offset:1024
	ds_read_b128 v[180:183], v138 offset:2048
	ds_read_b128 v[184:187], v138 offset:3072
	ds_read_b128 v[188:191], v138 offset:4096
	ds_read_b128 v[192:195], v138 offset:5120
	ds_read_b128 v[208:211], v138 offset:6144
	ds_read_b128 v[212:215], v138 offset:7168
	global_load_lds_dwordx4 v[196:197], off
	v_lshl_add_u64 v[196:197], s[56:57], 0, v[134:135]
	s_mov_b32 m0, s92
	s_nop 0
	global_load_lds_dwordx4 v[196:197], off
	s_waitcnt vmcnt(8)
	s_waitcnt lgkmcnt(0)
	s_barrier
	s_setprio 1
	v_mfma_f32_16x16x32_bf16 v[128:131], v[140:143], v[172:175], v[128:131]
	v_mfma_f32_16x16x32_bf16 v[124:127], v[148:151], v[172:175], v[124:127]
	v_mfma_f32_16x16x32_bf16 v[120:123], v[140:143], v[180:183], v[120:123]
	v_mfma_f32_16x16x32_bf16 v[112:115], v[148:151], v[180:183], v[112:115]
	v_mfma_f32_16x16x32_bf16 v[104:107], v[140:143], v[188:191], v[104:107]
	v_mfma_f32_16x16x32_bf16 v[96:99], v[148:151], v[188:191], v[96:99]
	v_mfma_f32_16x16x32_bf16 v[88:91], v[140:143], v[208:211], v[88:91]
	v_mfma_f32_16x16x32_bf16 v[80:83], v[148:151], v[208:211], v[80:83]
	v_mfma_f32_16x16x32_bf16 v[128:131], v[144:147], v[176:179], v[128:131]
	v_mfma_f32_16x16x32_bf16 v[124:127], v[152:155], v[176:179], v[124:127]
	v_mfma_f32_16x16x32_bf16 v[120:123], v[144:147], v[184:187], v[120:123]
	v_mfma_f32_16x16x32_bf16 v[112:115], v[152:155], v[184:187], v[112:115]
	v_mfma_f32_16x16x32_bf16 v[104:107], v[144:147], v[192:195], v[104:107]
	v_mfma_f32_16x16x32_bf16 v[96:99], v[152:155], v[192:195], v[96:99]
	v_mfma_f32_16x16x32_bf16 v[88:91], v[144:147], v[212:215], v[88:91]
	v_mfma_f32_16x16x32_bf16 v[80:83], v[152:155], v[212:215], v[80:83]
	v_mfma_f32_16x16x32_bf16 v[116:119], v[156:159], v[172:175], v[116:119]
	v_mfma_f32_16x16x32_bf16 v[108:111], v[164:167], v[172:175], v[108:111]
	v_mfma_f32_16x16x32_bf16 v[100:103], v[156:159], v[180:183], v[100:103]
	v_mfma_f32_16x16x32_bf16 v[92:95], v[164:167], v[180:183], v[92:95]
	v_mfma_f32_16x16x32_bf16 v[84:87], v[156:159], v[188:191], v[84:87]
	v_mfma_f32_16x16x32_bf16 v[76:79], v[164:167], v[188:191], v[76:79]
	v_mfma_f32_16x16x32_bf16 v[72:75], v[156:159], v[208:211], v[72:75]
	v_mfma_f32_16x16x32_bf16 v[68:71], v[164:167], v[208:211], v[68:71]
	v_mfma_f32_16x16x32_bf16 v[116:119], v[160:163], v[176:179], v[116:119]
	v_mfma_f32_16x16x32_bf16 v[108:111], v[168:171], v[176:179], v[108:111]
	v_mfma_f32_16x16x32_bf16 v[100:103], v[160:163], v[184:187], v[100:103]
	v_mfma_f32_16x16x32_bf16 v[92:95], v[168:171], v[184:187], v[92:95]
	v_mfma_f32_16x16x32_bf16 v[84:87], v[160:163], v[192:195], v[84:87]
	v_mfma_f32_16x16x32_bf16 v[76:79], v[168:171], v[192:195], v[76:79]
	v_mfma_f32_16x16x32_bf16 v[72:75], v[160:163], v[212:215], v[72:75]
	v_mfma_f32_16x16x32_bf16 v[68:71], v[168:171], v[212:215], v[68:71]
	s_setprio 0
	s_barrier
	s_mov_b32 m0, s89
	v_lshl_add_u64 v[196:197], s[38:39], 0, v[18:19]
	ds_read_b128 v[172:175], v138 offset:16384
	ds_read_b128 v[176:179], v138 offset:17408
	ds_read_b128 v[180:183], v138 offset:18432
	ds_read_b128 v[184:187], v138 offset:19456
	ds_read_b128 v[188:191], v138 offset:20480
	ds_read_b128 v[192:195], v138 offset:21504
	ds_read_b128 v[208:211], v138 offset:22528
	ds_read_b128 v[212:215], v138 offset:23552
	global_load_lds_dwordx4 v[196:197], off
	v_lshl_add_u64 v[216:217], s[38:39], 0, v[136:137]
	s_mov_b32 m0, s86
	v_lshl_add_u64 v[218:219], s[46:47], 0, v[18:19]
	global_load_lds_dwordx4 v[216:217], off
	s_mov_b32 m0, s88
	v_lshl_add_u64 v[220:221], s[36:37], 0, v[134:135]
	global_load_lds_dwordx4 v[218:219], off
	v_lshl_add_u64 v[218:219], s[46:47], 0, v[136:137]
	s_mov_b32 m0, s87
	s_nop 0
	global_load_lds_dwordx4 v[218:219], off
	v_lshl_add_u64 v[218:219], s[36:37], 0, v[132:133]
	s_mov_b32 m0, s23
	s_nop 0
	global_load_lds_dwordx4 v[218:219], off
	s_mov_b32 m0, s62
	s_nop 0
	global_load_lds_dwordx4 v[220:221], off
	s_waitcnt vmcnt(8)
	s_waitcnt lgkmcnt(0)
	s_barrier
; #define PG8_STAGE(bufoff, gbase, voff) do { _Pragma("unroll") for (int _i = 0; _i < 2; ++_i) \
;         __builtin_amdgcn_global_load_lds((const unsigned*)((const char*)(gbase) + (voff)[_i]), (LAS unsigned*)(lds + (bufoff) + ldsw + _i * 8192), 16, 0, 0); } while (0)
; #define PG8_LDA(dst, b, h) do { _Pragma("unroll") for (int m = 0; m < 4; ++m) _Pragma("unroll") for (int k = 0; k < 2; ++k) dst[m][k] = *(const LAS bf16x8*)(lds + PG8_SA(b, h) + aoff + m * 2048 + k * 1024); } while (0)
; #define PG8_LDB(dst, b, h) do { _Pragma("unroll") for (int n = 0; n < 2; ++n) _Pragma("unroll") for (int k = 0; k < 2; ++k) dst[n][k] = *(const LAS bf16x8*)(lds + PG8_SB(b, h) + boff + n * 2048 + k * 1024); } while (0)
; #define PG8_MMA(ai, bj, At, Bt) do { __builtin_amdgcn_s_setprio(1); _Pragma("unroll") for (int m = 0; m < 4; ++m) _Pragma("unroll") for (int n = 0; n < 2; ++n) _Pragma("unroll") for (int k = 0; k < 2; ++k) \
;         acc[ai][bj][m][n] = __builtin_amdgcn_mfma_f32_16x16x32_bf16(Bt[n][k], At[m][k], acc[ai][bj][m][n], 0, 0, 0); __builtin_amdgcn_s_setprio(0); } while (0)
; #define PG8_WAIT_V(n) asm volatile("s_waitcnt vmcnt(" #n ")" ::: "memory")
; #define PG8_WAIT_L(n) asm volatile("s_waitcnt lgkmcnt(" #n ")" ::: "memory")
; #define PG8_BAR __builtin_amdgcn_s_barrier()
; #define PG8_SCHED __builtin_amdgcn_sched_barrier(0)
; template <class Epi, class Sched, bool HALFN = false>
; __device__ __forceinline__ void gemm_phase(LAS unsigned char* lds, const Gemm g, const Sched& S, const Epi& E, int wave_s) {
;     ...
;             PG8_LDA(At, 0, 1); PG8_STAGE(PG8_SB(0, 0), b2, voffB); PG8_STAGE(PG8_SB(0, 1), b2 + bh1, voffB); PG8_STAGE(PG8_SA(0, 0), a2, voffA);
;             PG8_WAIT_V(8); PG8_WAIT_L(0); PG8_BAR; PG8_MMA(1, 0, At, B0); if (!HALFN) PG8_MMA(1, 1, At, B1); PG8_BAR; PG8_SCHED;
;             PG8_LDB(B0, 1, 0); if (!HALFN) PG8_LDB(B1, 1, 1); PG8_SCHED; PG8_LDA(At, 1, 0); PG8_STAGE(PG8_SA(0, 1), a2 + hstep, voffA);
;             PG8_WAIT_V(8); PG8_WAIT_L(0); PG8_BAR; PG8_MMA(0, 0, At, B0); if (!HALFN) PG8_MMA(0, 1, At, B1); PG8_BAR; PG8_SCHED;
	s_setprio 1
	v_mfma_f32_16x16x32_bf16 v[64:67], v[140:143], v[172:175], v[64:67]
	v_mfma_f32_16x16x32_bf16 v[60:63], v[148:151], v[172:175], v[60:63]
	v_mfma_f32_16x16x32_bf16 v[56:59], v[140:143], v[180:183], v[56:59]
	v_mfma_f32_16x16x32_bf16 v[48:51], v[148:151], v[180:183], v[48:51]
	v_mfma_f32_16x16x32_bf16 v[40:43], v[140:143], v[188:191], v[40:43]
	v_mfma_f32_16x16x32_bf16 v[32:35], v[148:151], v[188:191], v[32:35]
	v_mfma_f32_16x16x32_bf16 v[24:27], v[140:143], v[208:211], v[24:27]
	v_mfma_f32_16x16x32_bf16 v[14:17], v[148:151], v[208:211], v[14:17]
	v_mfma_f32_16x16x32_bf16 v[64:67], v[144:147], v[176:179], v[64:67]
	v_mfma_f32_16x16x32_bf16 v[60:63], v[152:155], v[176:179], v[60:63]
	v_mfma_f32_16x16x32_bf16 v[56:59], v[144:147], v[184:187], v[56:59]
	v_mfma_f32_16x16x32_bf16 v[48:51], v[152:155], v[184:187], v[48:51]
	v_mfma_f32_16x16x32_bf16 v[40:43], v[144:147], v[192:195], v[40:43]
	v_mfma_f32_16x16x32_bf16 v[32:35], v[152:155], v[192:195], v[32:35]
	v_mfma_f32_16x16x32_bf16 v[24:27], v[144:147], v[212:215], v[24:27]
	v_mfma_f32_16x16x32_bf16 v[14:17], v[152:155], v[212:215], v[14:17]
	v_mfma_f32_16x16x32_bf16 v[52:55], v[156:159], v[172:175], v[52:55]
	v_mfma_f32_16x16x32_bf16 v[44:47], v[164:167], v[172:175], v[44:47]
	v_mfma_f32_16x16x32_bf16 v[36:39], v[156:159], v[180:183], v[36:39]
	v_mfma_f32_16x16x32_bf16 v[28:31], v[164:167], v[180:183], v[28:31]
	v_mfma_f32_16x16x32_bf16 v[20:23], v[156:159], v[188:191], v[20:23]
	v_mfma_f32_16x16x32_bf16 v[10:13], v[164:167], v[188:191], v[10:13]
	v_mfma_f32_16x16x32_bf16 v[6:9], v[156:159], v[208:211], v[6:9]
	v_mfma_f32_16x16x32_bf16 v[2:5], v[164:167], v[208:211], v[2:5]
	v_mfma_f32_16x16x32_bf16 v[52:55], v[160:163], v[176:179], v[52:55]
	v_mfma_f32_16x16x32_bf16 v[44:47], v[168:171], v[176:179], v[44:47]
	v_mfma_f32_16x16x32_bf16 v[36:39], v[160:163], v[184:187], v[36:39]
	v_mfma_f32_16x16x32_bf16 v[28:31], v[168:171], v[184:187], v[28:31]
	v_mfma_f32_16x16x32_bf16 v[20:23], v[160:163], v[192:195], v[20:23]
	v_mfma_f32_16x16x32_bf16 v[10:13], v[168:171], v[192:195], v[10:13]
	v_mfma_f32_16x16x32_bf16 v[6:9], v[160:163], v[212:215], v[6:9]
	v_mfma_f32_16x16x32_bf16 v[2:5], v[168:171], v[212:215], v[2:5]
	s_setprio 0
	s_barrier
	v_add_u32_e32 v139, s85, v1
	ds_read_b128 v[140:143], v139
	ds_read_b128 v[144:147], v139 offset:1024
	ds_read_b128 v[148:151], v139 offset:2048
	ds_read_b128 v[152:155], v139 offset:3072
	v_add_u32_e32 v139, s84, v1
	ds_read_b128 v[156:159], v139
	ds_read_b128 v[160:163], v139 offset:1024
	ds_read_b128 v[164:167], v139 offset:2048
	ds_read_b128 v[168:171], v139 offset:3072
	s_mov_b32 m0, s64
	v_lshl_add_u64 v[222:223], s[34:35], 0, v[132:133]
	ds_read_b128 v[172:175], v138 offset:32768
	ds_read_b128 v[176:179], v138 offset:33792
	ds_read_b128 v[180:183], v138 offset:34816
	ds_read_b128 v[184:187], v138 offset:35840
	ds_read_b128 v[188:191], v138 offset:36864
	ds_read_b128 v[192:195], v138 offset:37888
	ds_read_b128 v[208:211], v138 offset:38912
	ds_read_b128 v[212:215], v138 offset:39936
	global_load_lds_dwordx4 v[222:223], off
	v_lshl_add_u64 v[222:223], s[34:35], 0, v[134:135]
	s_mov_b32 m0, s65
	s_nop 0
	global_load_lds_dwordx4 v[222:223], off
	s_waitcnt vmcnt(8)
	s_waitcnt lgkmcnt(0)
	s_barrier
	s_setprio 1
	v_mfma_f32_16x16x32_bf16 v[128:131], v[140:143], v[172:175], v[128:131]
	v_mfma_f32_16x16x32_bf16 v[124:127], v[148:151], v[172:175], v[124:127]
	v_mfma_f32_16x16x32_bf16 v[120:123], v[140:143], v[180:183], v[120:123]
	v_mfma_f32_16x16x32_bf16 v[112:115], v[148:151], v[180:183], v[112:115]
	v_mfma_f32_16x16x32_bf16 v[104:107], v[140:143], v[188:191], v[104:107]
	v_mfma_f32_16x16x32_bf16 v[96:99], v[148:151], v[188:191], v[96:99]
	v_mfma_f32_16x16x32_bf16 v[88:91], v[140:143], v[208:211], v[88:91]
	v_mfma_f32_16x16x32_bf16 v[80:83], v[148:151], v[208:211], v[80:83]
	v_mfma_f32_16x16x32_bf16 v[128:131], v[144:147], v[176:179], v[128:131]
	v_mfma_f32_16x16x32_bf16 v[124:127], v[152:155], v[176:179], v[124:127]
	v_mfma_f32_16x16x32_bf16 v[120:123], v[144:147], v[184:187], v[120:123]
	v_mfma_f32_16x16x32_bf16 v[112:115], v[152:155], v[184:187], v[112:115]
	v_mfma_f32_16x16x32_bf16 v[104:107], v[144:147], v[192:195], v[104:107]
	v_mfma_f32_16x16x32_bf16 v[96:99], v[152:155], v[192:195], v[96:99]
	v_mfma_f32_16x16x32_bf16 v[88:91], v[144:147], v[212:215], v[88:91]
	v_mfma_f32_16x16x32_bf16 v[80:83], v[152:155], v[212:215], v[80:83]
	v_mfma_f32_16x16x32_bf16 v[116:119], v[156:159], v[172:175], v[116:119]
	v_mfma_f32_16x16x32_bf16 v[108:111], v[164:167], v[172:175], v[108:111]
	v_mfma_f32_16x16x32_bf16 v[100:103], v[156:159], v[180:183], v[100:103]
	v_mfma_f32_16x16x32_bf16 v[92:95], v[164:167], v[180:183], v[92:95]
	v_mfma_f32_16x16x32_bf16 v[84:87], v[156:159], v[188:191], v[84:87]
	v_mfma_f32_16x16x32_bf16 v[76:79], v[164:167], v[188:191], v[76:79]
	v_mfma_f32_16x16x32_bf16 v[72:75], v[156:159], v[208:211], v[72:75]
	v_mfma_f32_16x16x32_bf16 v[68:71], v[164:167], v[208:211], v[68:71]
	v_mfma_f32_16x16x32_bf16 v[116:119], v[160:163], v[176:179], v[116:119]
	v_mfma_f32_16x16x32_bf16 v[108:111], v[168:171], v[176:179], v[108:111]
	v_mfma_f32_16x16x32_bf16 v[100:103], v[160:163], v[184:187], v[100:103]
	v_mfma_f32_16x16x32_bf16 v[92:95], v[168:171], v[184:187], v[92:95]
	v_mfma_f32_16x16x32_bf16 v[84:87], v[160:163], v[192:195], v[84:87]
	v_mfma_f32_16x16x32_bf16 v[76:79], v[168:171], v[192:195], v[76:79]
	v_mfma_f32_16x16x32_bf16 v[72:75], v[160:163], v[212:215], v[72:75]
	v_mfma_f32_16x16x32_bf16 v[68:71], v[168:171], v[212:215], v[68:71]
	s_setprio 0
	s_barrier
; #define PG8_STAGE(bufoff, gbase, voff) do { _Pragma("unroll") for (int _i = 0; _i < 2; ++_i) \
;         __builtin_amdgcn_global_load_lds((const unsigned*)((const char*)(gbase) + (voff)[_i]), (LAS unsigned*)(lds + (bufoff) + ldsw + _i * 8192), 16, 0, 0); } while (0)
; #define PG8_LDA(dst, b, h) do { _Pragma("unroll") for (int m = 0; m < 4; ++m) _Pragma("unroll") for (int k = 0; k < 2; ++k) dst[m][k] = *(const LAS bf16x8*)(lds + PG8_SA(b, h) + aoff + m * 2048 + k * 1024); } while (0)
; #define PG8_MMA(ai, bj, At, Bt) do { __builtin_amdgcn_s_setprio(1); _Pragma("unroll") for (int m = 0; m < 4; ++m) _Pragma("unroll") for (int n = 0; n < 2; ++n) _Pragma("unroll") for (int k = 0; k < 2; ++k) \
;         acc[ai][bj][m][n] = __builtin_amdgcn_mfma_f32_16x16x32_bf16(Bt[n][k], At[m][k], acc[ai][bj][m][n], 0, 0, 0); __builtin_amdgcn_s_setprio(0); } while (0)
; #define PG8_WAIT_V(n) asm volatile("s_waitcnt vmcnt(" #n ")" ::: "memory")
; #define PG8_WAIT_L(n) asm volatile("s_waitcnt lgkmcnt(" #n ")" ::: "memory")
; #define PG8_BAR __builtin_amdgcn_s_barrier()
; #define PG8_SCHED __builtin_amdgcn_sched_barrier(0)
; template <class Epi, class Sched, bool HALFN = false>
; __device__ __forceinline__ void gemm_phase(LAS unsigned char* lds, const Gemm g, const Sched& S, const Epi& E, int wave_s) {
;     ...
;             PG8_LDA(At, 1, 1); PG8_STAGE(PG8_SB(1, 0), b3, voffB); PG8_STAGE(PG8_SB(1, 1), b3 + bh1, voffB); PG8_STAGE(PG8_SA(1, 0), a3, voffA);
;             PG8_WAIT_V(8); PG8_WAIT_L(0); PG8_BAR; PG8_MMA(1, 0, At, B0); if (!HALFN) PG8_MMA(1, 1, At, B1); PG8_BAR; PG8_SCHED;
;         }
;         if (wr == 0) PG8_BAR;
	s_mov_b32 m0, s83
	v_lshl_add_u64 v[196:197], v[196:197], 0, s[50:51]
	ds_read_b128 v[172:175], v138 offset:49152
	ds_read_b128 v[176:179], v138 offset:50176
	ds_read_b128 v[180:183], v138 offset:51200
	ds_read_b128 v[184:187], v138 offset:52224
	ds_read_b128 v[188:191], v138 offset:53248
	ds_read_b128 v[192:195], v138 offset:54272
	ds_read_b128 v[208:211], v138 offset:55296
	ds_read_b128 v[212:215], v138 offset:56320
	global_load_lds_dwordx4 v[196:197], off
	v_lshl_add_u64 v[196:197], v[216:217], 0, s[50:51]
	s_mov_b32 m0, s82
	s_nop 0
	global_load_lds_dwordx4 v[196:197], off
	v_lshl_add_u64 v[196:197], s[30:31], 0, v[18:19]
	s_mov_b32 m0, s91
	s_nop 0
	global_load_lds_dwordx4 v[196:197], off
	v_lshl_add_u64 v[196:197], s[30:31], 0, v[136:137]
	s_mov_b32 m0, s90
	s_nop 0
	global_load_lds_dwordx4 v[196:197], off
	v_lshl_add_u64 v[196:197], v[218:219], 0, s[50:51]
	s_mov_b32 m0, s66
	s_nop 0
	global_load_lds_dwordx4 v[196:197], off
	v_lshl_add_u64 v[196:197], v[220:221], 0, s[50:51]
	s_mov_b32 m0, s67
	s_nop 0
	global_load_lds_dwordx4 v[196:197], off
	s_waitcnt vmcnt(8)
	s_waitcnt lgkmcnt(0)
	s_barrier
	s_setprio 1
	v_mfma_f32_16x16x32_bf16 v[64:67], v[140:143], v[172:175], v[64:67]
	v_mfma_f32_16x16x32_bf16 v[60:63], v[148:151], v[172:175], v[60:63]
	v_mfma_f32_16x16x32_bf16 v[56:59], v[140:143], v[180:183], v[56:59]
	v_mfma_f32_16x16x32_bf16 v[48:51], v[148:151], v[180:183], v[48:51]
	v_mfma_f32_16x16x32_bf16 v[40:43], v[140:143], v[188:191], v[40:43]
	v_mfma_f32_16x16x32_bf16 v[32:35], v[148:151], v[188:191], v[32:35]
	v_mfma_f32_16x16x32_bf16 v[24:27], v[140:143], v[208:211], v[24:27]
	v_mfma_f32_16x16x32_bf16 v[14:17], v[148:151], v[208:211], v[14:17]
	v_mfma_f32_16x16x32_bf16 v[64:67], v[144:147], v[176:179], v[64:67]
	v_mfma_f32_16x16x32_bf16 v[60:63], v[152:155], v[176:179], v[60:63]
	v_mfma_f32_16x16x32_bf16 v[56:59], v[144:147], v[184:187], v[56:59]
	v_mfma_f32_16x16x32_bf16 v[48:51], v[152:155], v[184:187], v[48:51]
	v_mfma_f32_16x16x32_bf16 v[40:43], v[144:147], v[192:195], v[40:43]
	v_mfma_f32_16x16x32_bf16 v[32:35], v[152:155], v[192:195], v[32:35]
	v_mfma_f32_16x16x32_bf16 v[24:27], v[144:147], v[212:215], v[24:27]
	v_mfma_f32_16x16x32_bf16 v[14:17], v[152:155], v[212:215], v[14:17]
	v_mfma_f32_16x16x32_bf16 v[52:55], v[156:159], v[172:175], v[52:55]
	v_mfma_f32_16x16x32_bf16 v[44:47], v[164:167], v[172:175], v[44:47]
	v_mfma_f32_16x16x32_bf16 v[36:39], v[156:159], v[180:183], v[36:39]
	v_mfma_f32_16x16x32_bf16 v[28:31], v[164:167], v[180:183], v[28:31]
	v_mfma_f32_16x16x32_bf16 v[20:23], v[156:159], v[188:191], v[20:23]
	v_mfma_f32_16x16x32_bf16 v[10:13], v[164:167], v[188:191], v[10:13]
	v_mfma_f32_16x16x32_bf16 v[6:9], v[156:159], v[208:211], v[6:9]
	v_mfma_f32_16x16x32_bf16 v[2:5], v[164:167], v[208:211], v[2:5]
	v_mfma_f32_16x16x32_bf16 v[52:55], v[160:163], v[176:179], v[52:55]
	v_mfma_f32_16x16x32_bf16 v[44:47], v[168:171], v[176:179], v[44:47]
	v_mfma_f32_16x16x32_bf16 v[36:39], v[160:163], v[184:187], v[36:39]
	v_mfma_f32_16x16x32_bf16 v[28:31], v[168:171], v[184:187], v[28:31]
	v_mfma_f32_16x16x32_bf16 v[20:23], v[160:163], v[192:195], v[20:23]
	v_mfma_f32_16x16x32_bf16 v[10:13], v[168:171], v[192:195], v[10:13]
	v_mfma_f32_16x16x32_bf16 v[6:9], v[160:163], v[212:215], v[6:9]
	v_mfma_f32_16x16x32_bf16 v[2:5], v[168:171], v[212:215], v[2:5]
	s_setprio 0
	s_barrier
	s_movk_i32 s34, 0x100
	s_andn2_b64 vcc, exec, s[28:29]
	s_mov_b64 s[30:31], -1
	s_mov_b64 s[28:29], 0
	s_cbranch_vccz .LBB0_515
	s_and_b64 vcc, exec, s[12:13]
	s_cbranch_vccz .LBB0_518
	s_barrier

; #define PG8_STAGE(bufoff, gbase, voff) do { _Pragma("unroll") for (int _i = 0; _i < 2; ++_i) \
;         __builtin_amdgcn_global_load_lds((const unsigned*)((const char*)(gbase) + (voff)[_i]), (LAS unsigned*)(lds + (bufoff) + ldsw + _i * 8192), 16, 0, 0); } while (0)
; #define PG8_LDA(dst, b, h) do { _Pragma("unroll") for (int m = 0; m < 4; ++m) _Pragma("unroll") for (int k = 0; k < 2; ++k) dst[m][k] = *(const LAS bf16x8*)(lds + PG8_SA(b, h) + aoff + m * 2048 + k * 1024); } while (0)
; #define PG8_LDB(dst, b, h) do { _Pragma("unroll") for (int n = 0; n < 2; ++n) _Pragma("unroll") for (int k = 0; k < 2; ++k) dst[n][k] = *(const LAS bf16x8*)(lds + PG8_SB(b, h) + boff + n * 2048 + k * 1024); } while (0)
; #define PG8_WAIT_V(n) asm volatile("s_waitcnt vmcnt(" #n ")" ::: "memory")
; #define PG8_WAIT_L(n) asm volatile("s_waitcnt lgkmcnt(" #n ")" ::: "memory")
; #define PG8_BAR __builtin_amdgcn_s_barrier()
; #define PG8_SCHED __builtin_amdgcn_sched_barrier(0)
; template <class Epi, class Sched, bool HALFN = false>
; __device__ __forceinline__ void gemm_phase(LAS unsigned char* lds, const Gemm g, const Sched& S, const Epi& E, int wave_s) {
;     ...
;         const bool has_next = S.next(ui + 1, nxt);
;         const char* nA = has_next ? (const char*)g.A + (size_t)nxt.z * g.zA * 2 + (size_t)nxt.pm * tstep : cA; const char* nB = has_next ? (const char*)g.Bt + (size_t)nxt.z * g.zB * 2 + (size_t)nxt.pn * (HALFN ? hstep : tstep) : cB;
;         for (int t = 0; t < nt; t += 2) {
;             const bool last = (t == nt - 2);
;             const char* a1 = cA + (size_t)(t + 1) * kstep;
;             const char* a2 = last ? nA : cA + (size_t)(t + 2) * kstep; const char* b2 = last ? nB : cB + (size_t)(t + 2) * kstep;
;             const char* a3 = a2 + kstep; const char* b3 = b2 + kstep;
;             PG8_LDB(B0, 0, 0); if (!HALFN) PG8_LDB(B1, 0, 1); PG8_SCHED; PG8_LDA(At, 0, 0); PG8_STAGE(PG8_SA(1, 1), a1 + hstep, voffA);
;             PG8_WAIT_V(8); PG8_WAIT_L(0); PG8_BAR; PG8_MMA(0, 0, At, B0); if (!HALFN) PG8_MMA(0, 1, At, B1); PG8_BAR; PG8_SCHED;
;             PG8_LDA(At, 0, 1); PG8_STAGE(PG8_SB(0, 0), b2, voffB); PG8_STAGE(PG8_SB(0, 1), b2 + bh1, voffB); PG8_STAGE(PG8_SA(0, 0), a2, voffA);
;             PG8_WAIT_V(8); PG8_WAIT_L(0); PG8_BAR; PG8_MMA(1, 0, At, B0); if (!HALFN) PG8_MMA(1, 1, At, B1); PG8_BAR; PG8_SCHED;
.LBB0_576:
	s_ashr_i32 s21, s20, 31
	s_lshl_b64 s[22:23], s[20:21], 16
	s_add_u32 s22, s36, s22
	s_addc_u32 s23, s37, s23
	s_and_b64 s[24:25], s[4:5], exec
	s_cselect_b32 s35, s23, s31
	s_cselect_b32 s34, s22, s30
	s_ashr_i32 s19, s18, 31
	s_lshl_b64 s[24:25], s[18:19], 16
	s_add_u32 s24, s38, s24
	s_addc_u32 s25, s39, s25
	s_and_b64 s[64:65], s[4:5], exec
	s_cselect_b32 s29, s25, s29
	s_cselect_b32 s28, s24, s28
	s_add_i32 s19, 0, 0x10000
	s_add_i32 s21, 0, 0x14000
	v_add_u32_e32 v14, s19, v1
	v_add_u32_e32 v32, s21, v1
	ds_read_b128 v[2:5], v14
	ds_read_b128 v[6:9], v14 offset:1024
	ds_read_b128 v[10:13], v14 offset:2048
	ds_read_b128 v[14:17], v14 offset:3072
	ds_read_b128 v[20:23], v32
	ds_read_b128 v[24:27], v32 offset:1024
	ds_read_b128 v[28:31], v32 offset:2048
	ds_read_b128 v[32:35], v32 offset:3072
	s_add_u32 s30, s30, 0x8080
	s_addc_u32 s31, s31, 0
	v_lshl_add_u64 v[68:69], s[30:31], 0, v[132:133]
	s_add_i32 m0, s27, 0xc000
	ds_read_b128 v[36:39], v138
	ds_read_b128 v[40:43], v138 offset:1024
	ds_read_b128 v[44:47], v138 offset:2048
	ds_read_b128 v[48:51], v138 offset:3072
	ds_read_b128 v[52:55], v138 offset:4096
	ds_read_b128 v[56:59], v138 offset:5120
	ds_read_b128 v[60:63], v138 offset:6144
	ds_read_b128 v[64:67], v138 offset:7168
	global_load_lds_dwordx4 v[68:69], off
	v_lshl_add_u64 v[68:69], s[30:31], 0, v[134:135]
	s_add_i32 m0, s27, 0xe000
	s_nop 0
	global_load_lds_dwordx4 v[68:69], off
	s_waitcnt vmcnt(8)
	s_waitcnt lgkmcnt(0)
	s_barrier
	s_setprio 1
	v_mfma_f32_16x16x32_bf16 v[68:71], v[2:5], v[36:39], 0
	v_mfma_f32_16x16x32_bf16 v[72:75], v[10:13], v[36:39], 0
	v_mfma_f32_16x16x32_bf16 v[76:79], v[2:5], v[44:47], 0
	v_mfma_f32_16x16x32_bf16 v[80:83], v[10:13], v[44:47], 0
	v_mfma_f32_16x16x32_bf16 v[84:87], v[2:5], v[52:55], 0
	v_mfma_f32_16x16x32_bf16 v[88:91], v[10:13], v[52:55], 0
	v_mfma_f32_16x16x32_bf16 v[92:95], v[2:5], v[60:63], 0
	v_mfma_f32_16x16x32_bf16 v[96:99], v[10:13], v[60:63], 0
	v_mfma_f32_16x16x32_bf16 v[68:71], v[6:9], v[40:43], v[68:71]
	v_mfma_f32_16x16x32_bf16 v[72:75], v[14:17], v[40:43], v[72:75]
	v_mfma_f32_16x16x32_bf16 v[76:79], v[6:9], v[48:51], v[76:79]
	v_mfma_f32_16x16x32_bf16 v[80:83], v[14:17], v[48:51], v[80:83]
	v_mfma_f32_16x16x32_bf16 v[84:87], v[6:9], v[56:59], v[84:87]
	v_mfma_f32_16x16x32_bf16 v[88:91], v[14:17], v[56:59], v[88:91]
	v_mfma_f32_16x16x32_bf16 v[92:95], v[6:9], v[64:67], v[92:95]
	v_mfma_f32_16x16x32_bf16 v[100:103], v[14:17], v[64:67], v[96:99]
	v_mfma_f32_16x16x32_bf16 v[96:99], v[20:23], v[36:39], 0
	v_mfma_f32_16x16x32_bf16 v[36:39], v[28:31], v[36:39], 0
	v_mfma_f32_16x16x32_bf16 v[108:111], v[24:27], v[40:43], v[96:99]
	v_mfma_f32_16x16x32_bf16 v[36:39], v[32:35], v[40:43], v[36:39]
	v_mfma_f32_16x16x32_bf16 v[40:43], v[20:23], v[44:47], 0
	v_mfma_f32_16x16x32_bf16 v[44:47], v[28:31], v[44:47], 0
	v_mfma_f32_16x16x32_bf16 v[40:43], v[24:27], v[48:51], v[40:43]
	v_mfma_f32_16x16x32_bf16 v[44:47], v[32:35], v[48:51], v[44:47]
	v_mfma_f32_16x16x32_bf16 v[48:51], v[20:23], v[52:55], 0
	v_mfma_f32_16x16x32_bf16 v[52:55], v[28:31], v[52:55], 0
	v_mfma_f32_16x16x32_bf16 v[48:51], v[24:27], v[56:59], v[48:51]
	v_mfma_f32_16x16x32_bf16 v[52:55], v[32:35], v[56:59], v[52:55]
	v_mfma_f32_16x16x32_bf16 v[56:59], v[20:23], v[60:63], 0
	v_mfma_f32_16x16x32_bf16 v[140:143], v[24:27], v[64:67], v[56:59]
	v_mfma_f32_16x16x32_bf16 v[56:59], v[28:31], v[60:63], 0
	v_mfma_f32_16x16x32_bf16 v[144:147], v[32:35], v[64:67], v[56:59]
	s_setprio 0
	s_barrier
	s_add_i32 s19, s19, s3
	v_lshl_add_u64 v[196:197], s[28:29], 0, v[18:19]
	s_mov_b32 m0, s19
	s_nop 1
	ds_read_b128 v[56:59], v138 offset:16384
	ds_read_b128 v[60:63], v138 offset:17408
	ds_read_b128 v[64:67], v138 offset:18432
	ds_read_b128 v[96:99], v138 offset:19456
	ds_read_b128 v[104:107], v138 offset:20480
	ds_read_b128 v[112:115], v138 offset:21504
	ds_read_b128 v[116:119], v138 offset:22528
	ds_read_b128 v[120:123], v138 offset:23552
	global_load_lds_dwordx4 v[196:197], off
	s_add_i32 m0, s19, 0x2000
	s_add_u32 s30, s28, 0x8000
	v_lshl_add_u64 v[252:253], s[28:29], 0, v[136:137]
	s_addc_u32 s31, s29, 0
	s_add_i32 s19, s21, s3
	global_load_lds_dwordx4 v[252:253], off
	v_lshl_add_u64 v[124:125], s[30:31], 0, v[18:19]
	s_mov_b32 m0, s19
	v_lshl_add_u64 v[202:203], s[34:35], 0, v[132:133]
	global_load_lds_dwordx4 v[124:125], off
	v_lshl_add_u64 v[124:125], s[30:31], 0, v[136:137]
	s_add_i32 m0, s19, 0x2000
	v_lshl_add_u64 v[198:199], s[34:35], 0, v[134:135]
	global_load_lds_dwordx4 v[124:125], off
	s_mov_b32 m0, s27
	s_nop 0
	global_load_lds_dwordx4 v[202:203], off
	s_mov_b32 m0, s41
	s_nop 0
	global_load_lds_dwordx4 v[198:199], off
	s_waitcnt vmcnt(8)
	s_waitcnt lgkmcnt(0)
	s_barrier
; #define PG8_STAGE(bufoff, gbase, voff) do { _Pragma("unroll") for (int _i = 0; _i < 2; ++_i) \
;         __builtin_amdgcn_global_load_lds((const unsigned*)((const char*)(gbase) + (voff)[_i]), (LAS unsigned*)(lds + (bufoff) + ldsw + _i * 8192), 16, 0, 0); } while (0)
; #define PG8_LDA(dst, b, h) do { _Pragma("unroll") for (int m = 0; m < 4; ++m) _Pragma("unroll") for (int k = 0; k < 2; ++k) dst[m][k] = *(const LAS bf16x8*)(lds + PG8_SA(b, h) + aoff + m * 2048 + k * 1024); } while (0)
; #define PG8_LDB(dst, b, h) do { _Pragma("unroll") for (int n = 0; n < 2; ++n) _Pragma("unroll") for (int k = 0; k < 2; ++k) dst[n][k] = *(const LAS bf16x8*)(lds + PG8_SB(b, h) + boff + n * 2048 + k * 1024); } while (0)
; #define PG8_MMA(ai, bj, At, Bt) do { __builtin_amdgcn_s_setprio(1); _Pragma("unroll") for (int m = 0; m < 4; ++m) _Pragma("unroll") for (int n = 0; n < 2; ++n) _Pragma("unroll") for (int k = 0; k < 2; ++k) \
;         acc[ai][bj][m][n] = __builtin_amdgcn_mfma_f32_16x16x32_bf16(Bt[n][k], At[m][k], acc[ai][bj][m][n], 0, 0, 0); __builtin_amdgcn_s_setprio(0); } while (0)
; #define PG8_WAIT_V(n) asm volatile("s_waitcnt vmcnt(" #n ")" ::: "memory")
; #define PG8_WAIT_L(n) asm volatile("s_waitcnt lgkmcnt(" #n ")" ::: "memory")
; #define PG8_BAR __builtin_amdgcn_s_barrier()
; #define PG8_SCHED __builtin_amdgcn_sched_barrier(0)
; template <class Epi, class Sched, bool HALFN = false>
; __device__ __forceinline__ void gemm_phase(LAS unsigned char* lds, const Gemm g, const Sched& S, const Epi& E, int wave_s) {
;     ...
;             PG8_LDA(At, 0, 1); PG8_STAGE(PG8_SB(0, 0), b2, voffB); PG8_STAGE(PG8_SB(0, 1), b2 + bh1, voffB); PG8_STAGE(PG8_SA(0, 0), a2, voffA);
;             PG8_WAIT_V(8); PG8_WAIT_L(0); PG8_BAR; PG8_MMA(1, 0, At, B0); if (!HALFN) PG8_MMA(1, 1, At, B1); PG8_BAR; PG8_SCHED;
;             PG8_LDB(B0, 1, 0); if (!HALFN) PG8_LDB(B1, 1, 1); PG8_SCHED; PG8_LDA(At, 1, 0); PG8_STAGE(PG8_SA(0, 1), a2 + hstep, voffA);
;             PG8_WAIT_V(8); PG8_WAIT_L(0); PG8_BAR; PG8_MMA(0, 0, At, B0); if (!HALFN) PG8_MMA(0, 1, At, B1); PG8_BAR; PG8_SCHED;
	s_setprio 1
	v_mfma_f32_16x16x32_bf16 v[124:127], v[2:5], v[56:59], 0
	v_mfma_f32_16x16x32_bf16 v[148:151], v[6:9], v[60:63], v[124:127]
	v_mfma_f32_16x16x32_bf16 v[124:127], v[10:13], v[56:59], 0
	v_mfma_f32_16x16x32_bf16 v[152:155], v[14:17], v[60:63], v[124:127]
	v_mfma_f32_16x16x32_bf16 v[124:127], v[2:5], v[64:67], 0
	v_mfma_f32_16x16x32_bf16 v[156:159], v[6:9], v[96:99], v[124:127]
	v_mfma_f32_16x16x32_bf16 v[124:127], v[10:13], v[64:67], 0
	v_mfma_f32_16x16x32_bf16 v[160:163], v[14:17], v[96:99], v[124:127]
	v_mfma_f32_16x16x32_bf16 v[124:127], v[2:5], v[104:107], 0
	v_mfma_f32_16x16x32_bf16 v[2:5], v[2:5], v[116:119], 0
	v_mfma_f32_16x16x32_bf16 v[164:167], v[6:9], v[112:115], v[124:127]
	v_mfma_f32_16x16x32_bf16 v[2:5], v[6:9], v[120:123], v[2:5]
	v_mfma_f32_16x16x32_bf16 v[6:9], v[10:13], v[116:119], 0
	v_mfma_f32_16x16x32_bf16 v[124:127], v[10:13], v[104:107], 0
	v_mfma_f32_16x16x32_bf16 v[6:9], v[14:17], v[120:123], v[6:9]
	v_mfma_f32_16x16x32_bf16 v[168:171], v[14:17], v[112:115], v[124:127]
	v_mfma_f32_16x16x32_bf16 v[14:17], v[28:31], v[56:59], 0
	v_mfma_f32_16x16x32_bf16 v[172:175], v[32:35], v[60:63], v[14:17]
	v_mfma_f32_16x16x32_bf16 v[14:17], v[20:23], v[64:67], 0
	v_mfma_f32_16x16x32_bf16 v[176:179], v[24:27], v[96:99], v[14:17]
	v_mfma_f32_16x16x32_bf16 v[14:17], v[28:31], v[64:67], 0
	v_mfma_f32_16x16x32_bf16 v[180:183], v[32:35], v[96:99], v[14:17]
	v_mfma_f32_16x16x32_bf16 v[14:17], v[20:23], v[104:107], 0
	v_mfma_f32_16x16x32_bf16 v[184:187], v[24:27], v[112:115], v[14:17]
	v_mfma_f32_16x16x32_bf16 v[14:17], v[28:31], v[104:107], 0
	v_mfma_f32_16x16x32_bf16 v[10:13], v[20:23], v[56:59], 0
	v_mfma_f32_16x16x32_bf16 v[188:191], v[32:35], v[112:115], v[14:17]
	v_mfma_f32_16x16x32_bf16 v[14:17], v[20:23], v[116:119], 0
	v_mfma_f32_16x16x32_bf16 v[10:13], v[24:27], v[60:63], v[10:13]
	v_mfma_f32_16x16x32_bf16 v[192:195], v[24:27], v[120:123], v[14:17]
	v_mfma_f32_16x16x32_bf16 v[14:17], v[28:31], v[116:119], 0
	v_mfma_f32_16x16x32_bf16 v[208:211], v[32:35], v[120:123], v[14:17]
	s_setprio 0
	s_barrier
	s_add_i32 s19, 0, 0x18000
	v_add_u32_e32 v24, s19, v1
	s_add_i32 s21, 0, 0x1c000
	s_nop 1
	ds_read_b128 v[14:17], v24
	ds_read_b128 v[20:23], v24 offset:1024
	ds_read_b128 v[28:31], v24 offset:2048
	ds_read_b128 v[212:215], v24 offset:3072
	v_add_u32_e32 v24, s21, v1
	ds_read_b128 v[216:219], v24
	ds_read_b128 v[220:223], v24 offset:1024
	ds_read_b128 v[224:227], v24 offset:2048
	ds_read_b128 v[228:231], v24 offset:3072
	s_add_u32 s30, s34, 0x8000
	s_addc_u32 s31, s35, 0
	s_mov_b32 m0, s42
	v_lshl_add_u64 v[56:57], s[30:31], 0, v[132:133]
	ds_read_b128 v[24:27], v138 offset:32768
	ds_read_b128 v[32:35], v138 offset:33792
	ds_read_b128 v[60:63], v138 offset:34816
	ds_read_b128 v[232:235], v138 offset:35840
	ds_read_b128 v[236:239], v138 offset:36864
	ds_read_b128 v[240:243], v138 offset:37888
	ds_read_b128 v[244:247], v138 offset:38912
	ds_read_b128 v[248:251], v138 offset:39936
	global_load_lds_dwordx4 v[56:57], off
	v_lshl_add_u64 v[56:57], s[30:31], 0, v[134:135]
	s_mov_b32 m0, s45
	s_nop 0
	global_load_lds_dwordx4 v[56:57], off
	s_waitcnt vmcnt(8)
	s_waitcnt lgkmcnt(0)
	s_barrier
	s_setprio 1
	v_mfma_f32_16x16x32_bf16 v[56:59], v[14:17], v[24:27], v[68:71]
	v_mfma_f32_16x16x32_bf16 v[128:131], v[20:23], v[32:35], v[56:59]
	v_mfma_f32_16x16x32_bf16 v[56:59], v[28:31], v[24:27], v[72:75]
	v_mfma_f32_16x16x32_bf16 v[124:127], v[212:215], v[32:35], v[56:59]
	v_mfma_f32_16x16x32_bf16 v[56:59], v[14:17], v[60:63], v[76:79]
	v_mfma_f32_16x16x32_bf16 v[112:115], v[20:23], v[232:235], v[56:59]
	v_mfma_f32_16x16x32_bf16 v[56:59], v[28:31], v[60:63], v[80:83]
	v_mfma_f32_16x16x32_bf16 v[104:107], v[212:215], v[232:235], v[56:59]
	v_mfma_f32_16x16x32_bf16 v[56:59], v[14:17], v[236:239], v[84:87]
	v_mfma_f32_16x16x32_bf16 v[96:99], v[20:23], v[240:243], v[56:59]
	v_mfma_f32_16x16x32_bf16 v[56:59], v[28:31], v[236:239], v[88:91]
	v_mfma_f32_16x16x32_bf16 v[88:91], v[212:215], v[240:243], v[56:59]
	v_mfma_f32_16x16x32_bf16 v[56:59], v[14:17], v[244:247], v[92:95]
	v_mfma_f32_16x16x32_bf16 v[64:67], v[20:23], v[248:251], v[56:59]
	v_mfma_f32_16x16x32_bf16 v[56:59], v[28:31], v[244:247], v[100:103]
	v_mfma_f32_16x16x32_bf16 v[56:59], v[212:215], v[248:251], v[56:59]
	v_mfma_f32_16x16x32_bf16 v[68:71], v[216:219], v[24:27], v[108:111]
	v_mfma_f32_16x16x32_bf16 v[24:27], v[224:227], v[24:27], v[36:39]
	v_mfma_f32_16x16x32_bf16 v[116:119], v[228:231], v[32:35], v[24:27]
	v_mfma_f32_16x16x32_bf16 v[24:27], v[216:219], v[60:63], v[40:43]
	v_mfma_f32_16x16x32_bf16 v[108:111], v[220:223], v[232:235], v[24:27]
	v_mfma_f32_16x16x32_bf16 v[24:27], v[224:227], v[60:63], v[44:47]
	v_mfma_f32_16x16x32_bf16 v[100:103], v[228:231], v[232:235], v[24:27]
	v_mfma_f32_16x16x32_bf16 v[24:27], v[216:219], v[236:239], v[48:51]
	v_mfma_f32_16x16x32_bf16 v[92:95], v[220:223], v[240:243], v[24:27]
	v_mfma_f32_16x16x32_bf16 v[24:27], v[224:227], v[236:239], v[52:55]
	v_mfma_f32_16x16x32_bf16 v[84:87], v[228:231], v[240:243], v[24:27]
	v_mfma_f32_16x16x32_bf16 v[24:27], v[216:219], v[244:247], v[140:143]
	v_mfma_f32_16x16x32_bf16 v[60:63], v[220:223], v[248:251], v[24:27]
	v_mfma_f32_16x16x32_bf16 v[24:27], v[224:227], v[244:247], v[144:147]
	v_mfma_f32_16x16x32_bf16 v[120:123], v[220:223], v[32:35], v[68:71]
	v_mfma_f32_16x16x32_bf16 v[52:55], v[228:231], v[248:251], v[24:27]
	s_setprio 0
	s_barrier
; #define PG8_STAGE(bufoff, gbase, voff) do { _Pragma("unroll") for (int _i = 0; _i < 2; ++_i) \
;         __builtin_amdgcn_global_load_lds((const unsigned*)((const char*)(gbase) + (voff)[_i]), (LAS unsigned*)(lds + (bufoff) + ldsw + _i * 8192), 16, 0, 0); } while (0)
; #define PG8_LDA(dst, b, h) do { _Pragma("unroll") for (int m = 0; m < 4; ++m) _Pragma("unroll") for (int k = 0; k < 2; ++k) dst[m][k] = *(const LAS bf16x8*)(lds + PG8_SA(b, h) + aoff + m * 2048 + k * 1024); } while (0)
; #define PG8_MMA(ai, bj, At, Bt) do { __builtin_amdgcn_s_setprio(1); _Pragma("unroll") for (int m = 0; m < 4; ++m) _Pragma("unroll") for (int n = 0; n < 2; ++n) _Pragma("unroll") for (int k = 0; k < 2; ++k) \
;         acc[ai][bj][m][n] = __builtin_amdgcn_mfma_f32_16x16x32_bf16(Bt[n][k], At[m][k], acc[ai][bj][m][n], 0, 0, 0); __builtin_amdgcn_s_setprio(0); } while (0)
; #define PG8_WAIT_V(n) asm volatile("s_waitcnt vmcnt(" #n ")" ::: "memory")
; #define PG8_WAIT_L(n) asm volatile("s_waitcnt lgkmcnt(" #n ")" ::: "memory")
; #define PG8_BAR __builtin_amdgcn_s_barrier()
; #define PG8_SCHED __builtin_amdgcn_sched_barrier(0)
; template <class Epi, class Sched, bool HALFN = false>
; __device__ __forceinline__ void gemm_phase(LAS unsigned char* lds, const Gemm g, const Sched& S, const Epi& E, int wave_s) {
;     ...
;             PG8_LDA(At, 1, 1); PG8_STAGE(PG8_SB(1, 0), b3, voffB); PG8_STAGE(PG8_SB(1, 1), b3 + bh1, voffB); PG8_STAGE(PG8_SA(1, 0), a3, voffA);
;             PG8_WAIT_V(8); PG8_WAIT_L(0); PG8_BAR; PG8_MMA(1, 0, At, B0); if (!HALFN) PG8_MMA(1, 1, At, B1); PG8_BAR; PG8_SCHED;
;         }
;         if (wr == 0) PG8_BAR;
	s_add_i32 s19, s19, s3
	s_nop 2
	v_lshl_add_u64 v[24:25], v[196:197], 0, s[50:51]
	s_mov_b32 m0, s19
	ds_read_b128 v[36:39], v138 offset:49152
	ds_read_b128 v[44:47], v138 offset:50176
	ds_read_b128 v[140:143], v138 offset:51200
	ds_read_b128 v[144:147], v138 offset:52224
	ds_read_b128 v[232:235], v138 offset:53248
	ds_read_b128 v[236:239], v138 offset:54272
	ds_read_b128 v[240:243], v138 offset:55296
	ds_read_b128 v[244:247], v138 offset:56320
	global_load_lds_dwordx4 v[24:25], off
	s_add_i32 m0, s19, 0x2000
	s_add_u32 s28, s28, 0x8080
	v_lshl_add_u64 v[24:25], v[252:253], 0, s[50:51]
	s_addc_u32 s29, s29, 0
	s_add_i32 s19, s21, s3
	global_load_lds_dwordx4 v[24:25], off
	v_lshl_add_u64 v[24:25], s[28:29], 0, v[18:19]
	s_mov_b32 m0, s19
	s_nop 0
	global_load_lds_dwordx4 v[24:25], off
	v_lshl_add_u64 v[24:25], s[28:29], 0, v[136:137]
	s_add_i32 m0, s19, 0x2000
	s_nop 0
	global_load_lds_dwordx4 v[24:25], off
	v_lshl_add_u64 v[24:25], v[202:203], 0, s[50:51]
	s_mov_b32 m0, s46
	s_nop 0
	global_load_lds_dwordx4 v[24:25], off
	v_lshl_add_u64 v[24:25], v[198:199], 0, s[50:51]
	s_mov_b32 m0, s47
	s_nop 0
	global_load_lds_dwordx4 v[24:25], off
	s_waitcnt vmcnt(8)
	s_waitcnt lgkmcnt(0)
	s_barrier
	s_setprio 1
	v_mfma_f32_16x16x32_bf16 v[24:27], v[14:17], v[36:39], v[148:151]
	v_mfma_f32_16x16x32_bf16 v[80:83], v[20:23], v[44:47], v[24:27]
	v_mfma_f32_16x16x32_bf16 v[24:27], v[28:31], v[36:39], v[152:155]
	v_mfma_f32_16x16x32_bf16 v[72:75], v[212:215], v[44:47], v[24:27]
	v_mfma_f32_16x16x32_bf16 v[24:27], v[14:17], v[140:143], v[156:159]
	v_mfma_f32_16x16x32_bf16 v[48:51], v[20:23], v[144:147], v[24:27]
	v_mfma_f32_16x16x32_bf16 v[24:27], v[28:31], v[140:143], v[160:163]
	v_mfma_f32_16x16x32_bf16 v[40:43], v[212:215], v[144:147], v[24:27]
	v_mfma_f32_16x16x32_bf16 v[24:27], v[14:17], v[232:235], v[164:167]
	v_mfma_f32_16x16x32_bf16 v[2:5], v[14:17], v[240:243], v[2:5]
	v_mfma_f32_16x16x32_bf16 v[32:35], v[20:23], v[236:239], v[24:27]
	v_mfma_f32_16x16x32_bf16 v[24:27], v[28:31], v[232:235], v[168:171]
	v_mfma_f32_16x16x32_bf16 v[14:17], v[20:23], v[244:247], v[2:5]
	v_mfma_f32_16x16x32_bf16 v[2:5], v[28:31], v[240:243], v[6:9]
	v_mfma_f32_16x16x32_bf16 v[24:27], v[212:215], v[236:239], v[24:27]
	v_mfma_f32_16x16x32_bf16 v[6:9], v[212:215], v[244:247], v[2:5]
	v_mfma_f32_16x16x32_bf16 v[2:5], v[216:219], v[36:39], v[10:13]
	v_mfma_f32_16x16x32_bf16 v[76:79], v[220:223], v[44:47], v[2:5]
	v_mfma_f32_16x16x32_bf16 v[2:5], v[224:227], v[36:39], v[172:175]
	v_mfma_f32_16x16x32_bf16 v[68:71], v[228:231], v[44:47], v[2:5]
	v_mfma_f32_16x16x32_bf16 v[2:5], v[216:219], v[140:143], v[176:179]
	v_mfma_f32_16x16x32_bf16 v[44:47], v[220:223], v[144:147], v[2:5]
	v_mfma_f32_16x16x32_bf16 v[2:5], v[224:227], v[140:143], v[180:183]
	v_mfma_f32_16x16x32_bf16 v[36:39], v[228:231], v[144:147], v[2:5]
	v_mfma_f32_16x16x32_bf16 v[2:5], v[216:219], v[232:235], v[184:187]
	v_mfma_f32_16x16x32_bf16 v[28:31], v[220:223], v[236:239], v[2:5]
	v_mfma_f32_16x16x32_bf16 v[2:5], v[224:227], v[232:235], v[188:191]
	v_mfma_f32_16x16x32_bf16 v[20:23], v[228:231], v[236:239], v[2:5]
	v_mfma_f32_16x16x32_bf16 v[2:5], v[216:219], v[240:243], v[192:195]
	v_mfma_f32_16x16x32_bf16 v[10:13], v[220:223], v[244:247], v[2:5]
	v_mfma_f32_16x16x32_bf16 v[2:5], v[224:227], v[240:243], v[208:211]
	v_mfma_f32_16x16x32_bf16 v[2:5], v[228:231], v[244:247], v[2:5]
	s_setprio 0
	s_barrier
	s_andn2_b64 vcc, exec, s[14:15]
	s_cbranch_vccnz .LBB0_578
	s_barrier

; #define PG8_STAGE(bufoff, gbase, voff) do { _Pragma("unroll") for (int _i = 0; _i < 2; ++_i) \
;         __builtin_amdgcn_global_load_lds((const unsigned*)((const char*)(gbase) + (voff)[_i]), (LAS unsigned*)(lds + (bufoff) + ldsw + _i * 8192), 16, 0, 0); } while (0)
; #define PG8_LDA(dst, b, h) do { _Pragma("unroll") for (int m = 0; m < 4; ++m) _Pragma("unroll") for (int k = 0; k < 2; ++k) dst[m][k] = *(const LAS bf16x8*)(lds + PG8_SA(b, h) + aoff + m * 2048 + k * 1024); } while (0)
; #define PG8_LDB(dst, b, h) do { _Pragma("unroll") for (int n = 0; n < 2; ++n) _Pragma("unroll") for (int k = 0; k < 2; ++k) dst[n][k] = *(const LAS bf16x8*)(lds + PG8_SB(b, h) + boff + n * 2048 + k * 1024); } while (0)
; #define PG8_WAIT_V(n) asm volatile("s_waitcnt vmcnt(" #n ")" ::: "memory")
; #define PG8_WAIT_L(n) asm volatile("s_waitcnt lgkmcnt(" #n ")" ::: "memory")
; #define PG8_BAR __builtin_amdgcn_s_barrier()
; #define PG8_SCHED __builtin_amdgcn_sched_barrier(0)
; template <class Epi, class Sched, bool HALFN = false>
; __device__ __forceinline__ void gemm_phase(LAS unsigned char* lds, const Gemm g, const Sched& S, const Epi& E, int wave_s) {
;     ...
;         const bool has_next = S.next(ui + 1, nxt);
;         const char* nA = has_next ? (const char*)g.A + (size_t)nxt.z * g.zA * 2 + (size_t)nxt.pm * tstep : cA; const char* nB = has_next ? (const char*)g.Bt + (size_t)nxt.z * g.zB * 2 + (size_t)nxt.pn * (HALFN ? hstep : tstep) : cB;
;         for (int t = 0; t < nt; t += 2) {
;             const bool last = (t == nt - 2);
;             const char* a1 = cA + (size_t)(t + 1) * kstep;
;             const char* a2 = last ? nA : cA + (size_t)(t + 2) * kstep; const char* b2 = last ? nB : cB + (size_t)(t + 2) * kstep;
;             const char* a3 = a2 + kstep; const char* b3 = b2 + kstep;
;             PG8_LDB(B0, 0, 0); if (!HALFN) PG8_LDB(B1, 0, 1); PG8_SCHED; PG8_LDA(At, 0, 0); PG8_STAGE(PG8_SA(1, 1), a1 + hstep, voffA);
;             PG8_WAIT_V(8); PG8_WAIT_L(0); PG8_BAR; PG8_MMA(0, 0, At, B0); if (!HALFN) PG8_MMA(0, 1, At, B1); PG8_BAR; PG8_SCHED;
;             PG8_LDA(At, 0, 1); PG8_STAGE(PG8_SB(0, 0), b2, voffB); PG8_STAGE(PG8_SB(0, 1), b2 + bh1, voffB); PG8_STAGE(PG8_SA(0, 0), a2, voffA);
;             PG8_WAIT_V(8); PG8_WAIT_L(0); PG8_BAR; PG8_MMA(1, 0, At, B0); if (!HALFN) PG8_MMA(1, 1, At, B1); PG8_BAR; PG8_SCHED;
.LBB0_985:
	s_add_u32 s34, s6, 0xfffc0080
	s_addc_u32 s35, s7, -1
	s_add_i32 s53, 0, 0x10000
	s_cmp_eq_u32 s52, 12
	s_cselect_b32 s37, s5, s35
	s_cselect_b32 s36, s25, s34
	v_add_u32_e32 v18, s53, v1
	s_cselect_b32 s35, s23, s48
	s_cselect_b32 s34, s31, s42
	s_add_i32 s66, 0, 0x14000
	ds_read_b128 v[132:135], v18
	ds_read_b128 v[136:139], v18 offset:1024
	ds_read_b128 v[140:143], v18 offset:2048
	ds_read_b128 v[144:147], v18 offset:3072
	v_add_u32_e32 v18, s66, v1
	ds_read_b128 v[148:151], v18
	ds_read_b128 v[152:155], v18 offset:1024
	ds_read_b128 v[156:159], v18 offset:2048
	ds_read_b128 v[160:163], v18 offset:3072
	v_lshl_add_u64 v[198:199], s[6:7], 0, v[172:173]
	s_add_i32 m0, s45, 0xc000
	ds_read_b128 v[176:179], v184
	ds_read_b128 v[180:183], v184 offset:1024
	ds_read_b128 v[186:189], v184 offset:2048
	ds_read_b128 v[190:193], v184 offset:3072
	ds_read_b128 v[194:197], v184 offset:4096
	ds_read_b128 v[208:211], v184 offset:5120
	ds_read_b128 v[212:215], v184 offset:6144
	ds_read_b128 v[216:219], v184 offset:7168
	global_load_lds_dwordx4 v[198:199], off
	v_lshl_add_u64 v[198:199], s[6:7], 0, v[174:175]
	s_add_i32 m0, s45, 0xe000
	s_nop 0
	global_load_lds_dwordx4 v[198:199], off
	s_waitcnt vmcnt(8)
	s_waitcnt lgkmcnt(0)
	s_barrier
	s_setprio 1
	v_mfma_f32_16x16x32_bf16 v[128:131], v[132:135], v[176:179], v[128:131]
	v_mfma_f32_16x16x32_bf16 v[124:127], v[140:143], v[176:179], v[124:127]
	v_mfma_f32_16x16x32_bf16 v[112:115], v[132:135], v[186:189], v[112:115]
	v_mfma_f32_16x16x32_bf16 v[108:111], v[140:143], v[186:189], v[108:111]
	v_mfma_f32_16x16x32_bf16 v[96:99], v[132:135], v[194:197], v[96:99]
	v_mfma_f32_16x16x32_bf16 v[92:95], v[140:143], v[194:197], v[92:95]
	v_mfma_f32_16x16x32_bf16 v[80:83], v[132:135], v[212:215], v[80:83]
	v_mfma_f32_16x16x32_bf16 v[76:79], v[140:143], v[212:215], v[76:79]
	v_mfma_f32_16x16x32_bf16 v[128:131], v[136:139], v[180:183], v[128:131]
	v_mfma_f32_16x16x32_bf16 v[124:127], v[144:147], v[180:183], v[124:127]
	v_mfma_f32_16x16x32_bf16 v[112:115], v[136:139], v[190:193], v[112:115]
	v_mfma_f32_16x16x32_bf16 v[108:111], v[144:147], v[190:193], v[108:111]
	v_mfma_f32_16x16x32_bf16 v[96:99], v[136:139], v[208:211], v[96:99]
	v_mfma_f32_16x16x32_bf16 v[92:95], v[144:147], v[208:211], v[92:95]
	v_mfma_f32_16x16x32_bf16 v[80:83], v[136:139], v[216:219], v[80:83]
	v_mfma_f32_16x16x32_bf16 v[76:79], v[144:147], v[216:219], v[76:79]
	v_mfma_f32_16x16x32_bf16 v[120:123], v[148:151], v[176:179], v[120:123]
	v_mfma_f32_16x16x32_bf16 v[116:119], v[156:159], v[176:179], v[116:119]
	v_mfma_f32_16x16x32_bf16 v[104:107], v[148:151], v[186:189], v[104:107]
	v_mfma_f32_16x16x32_bf16 v[100:103], v[156:159], v[186:189], v[100:103]
	v_mfma_f32_16x16x32_bf16 v[88:91], v[148:151], v[194:197], v[88:91]
	v_mfma_f32_16x16x32_bf16 v[84:87], v[156:159], v[194:197], v[84:87]
	v_mfma_f32_16x16x32_bf16 v[72:75], v[148:151], v[212:215], v[72:75]
	v_mfma_f32_16x16x32_bf16 v[68:71], v[156:159], v[212:215], v[68:71]
	v_mfma_f32_16x16x32_bf16 v[120:123], v[152:155], v[180:183], v[120:123]
	v_mfma_f32_16x16x32_bf16 v[116:119], v[160:163], v[180:183], v[116:119]
	v_mfma_f32_16x16x32_bf16 v[104:107], v[152:155], v[190:193], v[104:107]
	v_mfma_f32_16x16x32_bf16 v[100:103], v[160:163], v[190:193], v[100:103]
	v_mfma_f32_16x16x32_bf16 v[88:91], v[152:155], v[208:211], v[88:91]
	v_mfma_f32_16x16x32_bf16 v[84:87], v[160:163], v[208:211], v[84:87]
	v_mfma_f32_16x16x32_bf16 v[72:75], v[152:155], v[216:219], v[72:75]
	v_mfma_f32_16x16x32_bf16 v[68:71], v[160:163], v[216:219], v[68:71]
	s_setprio 0
	s_barrier
	s_add_i32 s53, s53, s41
	v_lshl_add_u64 v[198:199], s[34:35], 0, v[166:167]
	s_mov_b32 m0, s53
	ds_read_b128 v[176:179], v184 offset:16384
	ds_read_b128 v[180:183], v184 offset:17408
	ds_read_b128 v[186:189], v184 offset:18432
	ds_read_b128 v[190:193], v184 offset:19456
	ds_read_b128 v[194:197], v184 offset:20480
	ds_read_b128 v[208:211], v184 offset:21504
	ds_read_b128 v[212:215], v184 offset:22528
	ds_read_b128 v[216:219], v184 offset:23552
	global_load_lds_dwordx4 v[198:199], off
	s_add_i32 m0, s53, 0x2000
	s_add_u32 s76, s34, 0x40000
	v_lshl_add_u64 v[202:203], s[34:35], 0, v[170:171]
	s_addc_u32 s77, s35, 0
	s_add_i32 s53, s66, s41
	global_load_lds_dwordx4 v[202:203], off
	v_lshl_add_u64 v[220:221], s[76:77], 0, v[166:167]
	s_mov_b32 m0, s53
	v_lshl_add_u64 v[222:223], s[36:37], 0, v[168:169]
	global_load_lds_dwordx4 v[220:221], off
	v_lshl_add_u64 v[220:221], s[76:77], 0, v[170:171]
	s_add_i32 m0, s53, 0x2000
	s_nop 0
	global_load_lds_dwordx4 v[220:221], off
	v_lshl_add_u64 v[220:221], s[36:37], 0, v[164:165]
	s_mov_b32 m0, s45
	s_nop 0
	global_load_lds_dwordx4 v[220:221], off
	s_mov_b32 m0, s46
	s_nop 0
	global_load_lds_dwordx4 v[222:223], off
	s_waitcnt vmcnt(8)
	s_waitcnt lgkmcnt(0)
	s_barrier
; #define PG8_STAGE(bufoff, gbase, voff) do { _Pragma("unroll") for (int _i = 0; _i < 2; ++_i) \
;         __builtin_amdgcn_global_load_lds((const unsigned*)((const char*)(gbase) + (voff)[_i]), (LAS unsigned*)(lds + (bufoff) + ldsw + _i * 8192), 16, 0, 0); } while (0)
; #define PG8_LDA(dst, b, h) do { _Pragma("unroll") for (int m = 0; m < 4; ++m) _Pragma("unroll") for (int k = 0; k < 2; ++k) dst[m][k] = *(const LAS bf16x8*)(lds + PG8_SA(b, h) + aoff + m * 2048 + k * 1024); } while (0)
; #define PG8_LDB(dst, b, h) do { _Pragma("unroll") for (int n = 0; n < 2; ++n) _Pragma("unroll") for (int k = 0; k < 2; ++k) dst[n][k] = *(const LAS bf16x8*)(lds + PG8_SB(b, h) + boff + n * 2048 + k * 1024); } while (0)
; #define PG8_MMA(ai, bj, At, Bt) do { __builtin_amdgcn_s_setprio(1); _Pragma("unroll") for (int m = 0; m < 4; ++m) _Pragma("unroll") for (int n = 0; n < 2; ++n) _Pragma("unroll") for (int k = 0; k < 2; ++k) \
;         acc[ai][bj][m][n] = __builtin_amdgcn_mfma_f32_16x16x32_bf16(Bt[n][k], At[m][k], acc[ai][bj][m][n], 0, 0, 0); __builtin_amdgcn_s_setprio(0); } while (0)
; #define PG8_WAIT_V(n) asm volatile("s_waitcnt vmcnt(" #n ")" ::: "memory")
; #define PG8_WAIT_L(n) asm volatile("s_waitcnt lgkmcnt(" #n ")" ::: "memory")
; #define PG8_BAR __builtin_amdgcn_s_barrier()
; #define PG8_SCHED __builtin_amdgcn_sched_barrier(0)
; template <class Epi, class Sched, bool HALFN = false>
; __device__ __forceinline__ void gemm_phase(LAS unsigned char* lds, const Gemm g, const Sched& S, const Epi& E, int wave_s) {
;     ...
;             PG8_LDA(At, 0, 1); PG8_STAGE(PG8_SB(0, 0), b2, voffB); PG8_STAGE(PG8_SB(0, 1), b2 + bh1, voffB); PG8_STAGE(PG8_SA(0, 0), a2, voffA);
;             PG8_WAIT_V(8); PG8_WAIT_L(0); PG8_BAR; PG8_MMA(1, 0, At, B0); if (!HALFN) PG8_MMA(1, 1, At, B1); PG8_BAR; PG8_SCHED;
;             PG8_LDB(B0, 1, 0); if (!HALFN) PG8_LDB(B1, 1, 1); PG8_SCHED; PG8_LDA(At, 1, 0); PG8_STAGE(PG8_SA(0, 1), a2 + hstep, voffA);
;             PG8_WAIT_V(8); PG8_WAIT_L(0); PG8_BAR; PG8_MMA(0, 0, At, B0); if (!HALFN) PG8_MMA(0, 1, At, B1); PG8_BAR; PG8_SCHED;
	s_setprio 1
	v_mfma_f32_16x16x32_bf16 v[64:67], v[132:135], v[176:179], v[64:67]
	v_mfma_f32_16x16x32_bf16 v[60:63], v[140:143], v[176:179], v[60:63]
	v_mfma_f32_16x16x32_bf16 v[48:51], v[132:135], v[186:189], v[48:51]
	v_mfma_f32_16x16x32_bf16 v[44:47], v[140:143], v[186:189], v[44:47]
	v_mfma_f32_16x16x32_bf16 v[32:35], v[132:135], v[194:197], v[32:35]
	v_mfma_f32_16x16x32_bf16 v[28:31], v[140:143], v[194:197], v[28:31]
	v_mfma_f32_16x16x32_bf16 v[14:17], v[132:135], v[212:215], v[14:17]
	v_mfma_f32_16x16x32_bf16 v[10:13], v[140:143], v[212:215], v[10:13]
	v_mfma_f32_16x16x32_bf16 v[64:67], v[136:139], v[180:183], v[64:67]
	v_mfma_f32_16x16x32_bf16 v[60:63], v[144:147], v[180:183], v[60:63]
	v_mfma_f32_16x16x32_bf16 v[48:51], v[136:139], v[190:193], v[48:51]
	v_mfma_f32_16x16x32_bf16 v[44:47], v[144:147], v[190:193], v[44:47]
	v_mfma_f32_16x16x32_bf16 v[32:35], v[136:139], v[208:211], v[32:35]
	v_mfma_f32_16x16x32_bf16 v[28:31], v[144:147], v[208:211], v[28:31]
	v_mfma_f32_16x16x32_bf16 v[14:17], v[136:139], v[216:219], v[14:17]
	v_mfma_f32_16x16x32_bf16 v[10:13], v[144:147], v[216:219], v[10:13]
	v_mfma_f32_16x16x32_bf16 v[56:59], v[148:151], v[176:179], v[56:59]
	v_mfma_f32_16x16x32_bf16 v[52:55], v[156:159], v[176:179], v[52:55]
	v_mfma_f32_16x16x32_bf16 v[40:43], v[148:151], v[186:189], v[40:43]
	v_mfma_f32_16x16x32_bf16 v[36:39], v[156:159], v[186:189], v[36:39]
	v_mfma_f32_16x16x32_bf16 v[24:27], v[148:151], v[194:197], v[24:27]
	v_mfma_f32_16x16x32_bf16 v[20:23], v[156:159], v[194:197], v[20:23]
	v_mfma_f32_16x16x32_bf16 v[6:9], v[148:151], v[212:215], v[6:9]
	v_mfma_f32_16x16x32_bf16 v[2:5], v[156:159], v[212:215], v[2:5]
	v_mfma_f32_16x16x32_bf16 v[56:59], v[152:155], v[180:183], v[56:59]
	v_mfma_f32_16x16x32_bf16 v[52:55], v[160:163], v[180:183], v[52:55]
	v_mfma_f32_16x16x32_bf16 v[40:43], v[152:155], v[190:193], v[40:43]
	v_mfma_f32_16x16x32_bf16 v[36:39], v[160:163], v[190:193], v[36:39]
	v_mfma_f32_16x16x32_bf16 v[24:27], v[152:155], v[208:211], v[24:27]
	v_mfma_f32_16x16x32_bf16 v[20:23], v[160:163], v[208:211], v[20:23]
	v_mfma_f32_16x16x32_bf16 v[6:9], v[152:155], v[216:219], v[6:9]
	v_mfma_f32_16x16x32_bf16 v[2:5], v[160:163], v[216:219], v[2:5]
	s_setprio 0
	s_barrier
	s_add_i32 s53, 0, 0x18000
	v_add_u32_e32 v18, s53, v1
	s_add_i32 s66, 0, 0x1c000
	ds_read_b128 v[132:135], v18
	ds_read_b128 v[136:139], v18 offset:1024
	ds_read_b128 v[140:143], v18 offset:2048
	ds_read_b128 v[144:147], v18 offset:3072
	v_add_u32_e32 v18, s66, v1
	ds_read_b128 v[148:151], v18
	ds_read_b128 v[152:155], v18 offset:1024
	ds_read_b128 v[156:159], v18 offset:2048
	ds_read_b128 v[160:163], v18 offset:3072
	s_add_u32 s36, s36, 0x40000
	s_addc_u32 s37, s37, 0
	s_mov_b32 m0, s47
	v_lshl_add_u64 v[224:225], s[36:37], 0, v[164:165]
	ds_read_b128 v[176:179], v184 offset:32768
	ds_read_b128 v[180:183], v184 offset:33792
	ds_read_b128 v[186:189], v184 offset:34816
	ds_read_b128 v[190:193], v184 offset:35840
	ds_read_b128 v[194:197], v184 offset:36864
	ds_read_b128 v[208:211], v184 offset:37888
	ds_read_b128 v[212:215], v184 offset:38912
	ds_read_b128 v[216:219], v184 offset:39936
	global_load_lds_dwordx4 v[224:225], off
	v_lshl_add_u64 v[224:225], s[36:37], 0, v[168:169]
	s_mov_b32 m0, s55
	s_nop 0
	global_load_lds_dwordx4 v[224:225], off
	s_waitcnt vmcnt(8)
	s_waitcnt lgkmcnt(0)
	s_barrier
	s_setprio 1
	v_mfma_f32_16x16x32_bf16 v[128:131], v[132:135], v[176:179], v[128:131]
	v_mfma_f32_16x16x32_bf16 v[124:127], v[140:143], v[176:179], v[124:127]
	v_mfma_f32_16x16x32_bf16 v[112:115], v[132:135], v[186:189], v[112:115]
	v_mfma_f32_16x16x32_bf16 v[108:111], v[140:143], v[186:189], v[108:111]
	v_mfma_f32_16x16x32_bf16 v[96:99], v[132:135], v[194:197], v[96:99]
	v_mfma_f32_16x16x32_bf16 v[92:95], v[140:143], v[194:197], v[92:95]
	v_mfma_f32_16x16x32_bf16 v[80:83], v[132:135], v[212:215], v[80:83]
	v_mfma_f32_16x16x32_bf16 v[76:79], v[140:143], v[212:215], v[76:79]
	v_mfma_f32_16x16x32_bf16 v[128:131], v[136:139], v[180:183], v[128:131]
	v_mfma_f32_16x16x32_bf16 v[124:127], v[144:147], v[180:183], v[124:127]
	v_mfma_f32_16x16x32_bf16 v[112:115], v[136:139], v[190:193], v[112:115]
	v_mfma_f32_16x16x32_bf16 v[108:111], v[144:147], v[190:193], v[108:111]
	v_mfma_f32_16x16x32_bf16 v[96:99], v[136:139], v[208:211], v[96:99]
	v_mfma_f32_16x16x32_bf16 v[92:95], v[144:147], v[208:211], v[92:95]
	v_mfma_f32_16x16x32_bf16 v[80:83], v[136:139], v[216:219], v[80:83]
	v_mfma_f32_16x16x32_bf16 v[76:79], v[144:147], v[216:219], v[76:79]
	v_mfma_f32_16x16x32_bf16 v[120:123], v[148:151], v[176:179], v[120:123]
	v_mfma_f32_16x16x32_bf16 v[116:119], v[156:159], v[176:179], v[116:119]
	v_mfma_f32_16x16x32_bf16 v[104:107], v[148:151], v[186:189], v[104:107]
	v_mfma_f32_16x16x32_bf16 v[100:103], v[156:159], v[186:189], v[100:103]
	v_mfma_f32_16x16x32_bf16 v[88:91], v[148:151], v[194:197], v[88:91]
	v_mfma_f32_16x16x32_bf16 v[84:87], v[156:159], v[194:197], v[84:87]
	v_mfma_f32_16x16x32_bf16 v[72:75], v[148:151], v[212:215], v[72:75]
	v_mfma_f32_16x16x32_bf16 v[68:71], v[156:159], v[212:215], v[68:71]
	v_mfma_f32_16x16x32_bf16 v[120:123], v[152:155], v[180:183], v[120:123]
	v_mfma_f32_16x16x32_bf16 v[116:119], v[160:163], v[180:183], v[116:119]
	v_mfma_f32_16x16x32_bf16 v[104:107], v[152:155], v[190:193], v[104:107]
	v_mfma_f32_16x16x32_bf16 v[100:103], v[160:163], v[190:193], v[100:103]
	v_mfma_f32_16x16x32_bf16 v[88:91], v[152:155], v[208:211], v[88:91]
	v_mfma_f32_16x16x32_bf16 v[84:87], v[160:163], v[208:211], v[84:87]
	v_mfma_f32_16x16x32_bf16 v[72:75], v[152:155], v[216:219], v[72:75]
	v_mfma_f32_16x16x32_bf16 v[68:71], v[160:163], v[216:219], v[68:71]
	s_setprio 0
	s_barrier
; #define PG8_STAGE(bufoff, gbase, voff) do { _Pragma("unroll") for (int _i = 0; _i < 2; ++_i) \
;         __builtin_amdgcn_global_load_lds((const unsigned*)((const char*)(gbase) + (voff)[_i]), (LAS unsigned*)(lds + (bufoff) + ldsw + _i * 8192), 16, 0, 0); } while (0)
; #define PG8_LDA(dst, b, h) do { _Pragma("unroll") for (int m = 0; m < 4; ++m) _Pragma("unroll") for (int k = 0; k < 2; ++k) dst[m][k] = *(const LAS bf16x8*)(lds + PG8_SA(b, h) + aoff + m * 2048 + k * 1024); } while (0)
; #define PG8_MMA(ai, bj, At, Bt) do { __builtin_amdgcn_s_setprio(1); _Pragma("unroll") for (int m = 0; m < 4; ++m) _Pragma("unroll") for (int n = 0; n < 2; ++n) _Pragma("unroll") for (int k = 0; k < 2; ++k) \
;         acc[ai][bj][m][n] = __builtin_amdgcn_mfma_f32_16x16x32_bf16(Bt[n][k], At[m][k], acc[ai][bj][m][n], 0, 0, 0); __builtin_amdgcn_s_setprio(0); } while (0)
; #define PG8_WAIT_V(n) asm volatile("s_waitcnt vmcnt(" #n ")" ::: "memory")
; #define PG8_WAIT_L(n) asm volatile("s_waitcnt lgkmcnt(" #n ")" ::: "memory")
; #define PG8_BAR __builtin_amdgcn_s_barrier()
; #define PG8_SCHED __builtin_amdgcn_sched_barrier(0)
; template <class Epi, class Sched, bool HALFN = false>
; __device__ __forceinline__ void gemm_phase(LAS unsigned char* lds, const Gemm g, const Sched& S, const Epi& E, int wave_s) {
;     ...
;             PG8_LDA(At, 1, 1); PG8_STAGE(PG8_SB(1, 0), b3, voffB); PG8_STAGE(PG8_SB(1, 1), b3 + bh1, voffB); PG8_STAGE(PG8_SA(1, 0), a3, voffA);
;             PG8_WAIT_V(8); PG8_WAIT_L(0); PG8_BAR; PG8_MMA(1, 0, At, B0); if (!HALFN) PG8_MMA(1, 1, At, B1); PG8_BAR; PG8_SCHED;
;         }
	s_add_i32 s36, s53, s41
	v_lshl_add_u64 v[198:199], v[198:199], 0, s[50:51]
	s_mov_b32 m0, s36
	ds_read_b128 v[176:179], v184 offset:49152
	ds_read_b128 v[180:183], v184 offset:50176
	ds_read_b128 v[186:189], v184 offset:51200
	ds_read_b128 v[190:193], v184 offset:52224
	ds_read_b128 v[194:197], v184 offset:53248
	ds_read_b128 v[208:211], v184 offset:54272
	ds_read_b128 v[212:215], v184 offset:55296
	ds_read_b128 v[216:219], v184 offset:56320
	global_load_lds_dwordx4 v[198:199], off
	s_add_i32 m0, s36, 0x2000
	s_add_u32 s34, s34, 0x40080
	v_lshl_add_u64 v[198:199], v[202:203], 0, s[50:51]
	s_addc_u32 s35, s35, 0
	s_add_i32 s36, s66, s41
	global_load_lds_dwordx4 v[198:199], off
	v_lshl_add_u64 v[198:199], s[34:35], 0, v[166:167]
	s_mov_b32 m0, s36
	s_nop 0
	global_load_lds_dwordx4 v[198:199], off
	v_lshl_add_u64 v[198:199], s[34:35], 0, v[170:171]
	s_add_i32 m0, s36, 0x2000
	s_nop 0
	global_load_lds_dwordx4 v[198:199], off
	v_lshl_add_u64 v[198:199], v[220:221], 0, s[50:51]
	s_mov_b32 m0, s64
	s_nop 0
	global_load_lds_dwordx4 v[198:199], off
	v_lshl_add_u64 v[198:199], v[222:223], 0, s[50:51]
	s_mov_b32 m0, s65
	s_nop 0
	global_load_lds_dwordx4 v[198:199], off
	s_waitcnt vmcnt(8)
	s_waitcnt lgkmcnt(0)
	s_barrier
	s_setprio 1
	v_mfma_f32_16x16x32_bf16 v[64:67], v[132:135], v[176:179], v[64:67]
	v_mfma_f32_16x16x32_bf16 v[60:63], v[140:143], v[176:179], v[60:63]
	v_mfma_f32_16x16x32_bf16 v[48:51], v[132:135], v[186:189], v[48:51]
	v_mfma_f32_16x16x32_bf16 v[44:47], v[140:143], v[186:189], v[44:47]
	v_mfma_f32_16x16x32_bf16 v[32:35], v[132:135], v[194:197], v[32:35]
	v_mfma_f32_16x16x32_bf16 v[28:31], v[140:143], v[194:197], v[28:31]
	v_mfma_f32_16x16x32_bf16 v[14:17], v[132:135], v[212:215], v[14:17]
	v_mfma_f32_16x16x32_bf16 v[10:13], v[140:143], v[212:215], v[10:13]
	v_mfma_f32_16x16x32_bf16 v[64:67], v[136:139], v[180:183], v[64:67]
	v_mfma_f32_16x16x32_bf16 v[60:63], v[144:147], v[180:183], v[60:63]
	v_mfma_f32_16x16x32_bf16 v[48:51], v[136:139], v[190:193], v[48:51]
	v_mfma_f32_16x16x32_bf16 v[44:47], v[144:147], v[190:193], v[44:47]
	v_mfma_f32_16x16x32_bf16 v[32:35], v[136:139], v[208:211], v[32:35]
	v_mfma_f32_16x16x32_bf16 v[28:31], v[144:147], v[208:211], v[28:31]
	v_mfma_f32_16x16x32_bf16 v[14:17], v[136:139], v[216:219], v[14:17]
	v_mfma_f32_16x16x32_bf16 v[10:13], v[144:147], v[216:219], v[10:13]
	v_mfma_f32_16x16x32_bf16 v[56:59], v[148:151], v[176:179], v[56:59]
	v_mfma_f32_16x16x32_bf16 v[52:55], v[156:159], v[176:179], v[52:55]
	v_mfma_f32_16x16x32_bf16 v[40:43], v[148:151], v[186:189], v[40:43]
	v_mfma_f32_16x16x32_bf16 v[36:39], v[156:159], v[186:189], v[36:39]
	v_mfma_f32_16x16x32_bf16 v[24:27], v[148:151], v[194:197], v[24:27]
	v_mfma_f32_16x16x32_bf16 v[20:23], v[156:159], v[194:197], v[20:23]
	v_mfma_f32_16x16x32_bf16 v[6:9], v[148:151], v[212:215], v[6:9]
	v_mfma_f32_16x16x32_bf16 v[2:5], v[156:159], v[212:215], v[2:5]
	v_mfma_f32_16x16x32_bf16 v[56:59], v[152:155], v[180:183], v[56:59]
	v_mfma_f32_16x16x32_bf16 v[52:55], v[160:163], v[180:183], v[52:55]
	v_mfma_f32_16x16x32_bf16 v[40:43], v[152:155], v[190:193], v[40:43]
	v_mfma_f32_16x16x32_bf16 v[36:39], v[160:163], v[190:193], v[36:39]
	v_mfma_f32_16x16x32_bf16 v[24:27], v[152:155], v[208:211], v[24:27]
	v_mfma_f32_16x16x32_bf16 v[20:23], v[160:163], v[208:211], v[20:23]
	v_mfma_f32_16x16x32_bf16 v[6:9], v[152:155], v[216:219], v[6:9]
	v_mfma_f32_16x16x32_bf16 v[2:5], v[160:163], v[216:219], v[2:5]
	s_setprio 0
	s_add_i32 s52, s52, 2
	s_add_u32 s6, s6, 0x100
	s_addc_u32 s7, s7, 0
	s_add_u32 s42, s42, 0x100
	s_addc_u32 s48, s48, 0
	s_cmp_gt_u32 s52, 13
	s_barrier
	s_cbranch_scc0 .LBB0_985
	s_and_b64 vcc, exec, s[20:21]
	s_cbranch_vccz .LBB0_988
	s_barrier
